# v40: v37 without the pre-barrier lgkmcnt(8) waits in the GEMM K-loop phases 1/5 (all reads still waited for after the barrier)
# baseline (speedup 1.0000x reference)
; #define G_STAGE(bufoff, gbase, voff) do { _Pragma("unroll") for (int _i = 0; _i < 2; ++_i) \
;     __builtin_amdgcn_global_load_lds((const unsigned*)((const char*)(gbase) + (voff)[_i]), (LAS unsigned*)(lds + (bufoff) + ldsw + _i * 8192), 16, 0, 0); } while (0)
; #define G_LDA(dst, b, h) do { _Pragma("unroll") for (int m = 0; m < 4; ++m) _Pragma("unroll") for (int k = 0; k < 2; ++k) dst[m][k] = *(const LAS bf16x8*)(lds + G_SA(b, h) + aoff + m * 2048 + k * 1024); } while (0)
; #define G_LDB(dst, b, h) do { _Pragma("unroll") for (int n = 0; n < 2; ++n) _Pragma("unroll") for (int k = 0; k < 2; ++k) dst[n][k] = *(const LAS bf16x8*)(lds + G_SB(b, h) + boff + n * 2048 + k * 1024); } while (0)
; #define G_MMA(ai, bj, At, Bt) do { __builtin_amdgcn_s_setprio(1); _Pragma("unroll") for (int m = 0; m < 4; ++m) _Pragma("unroll") for (int n = 0; n < 2; ++n) _Pragma("unroll") for (int k = 0; k < 2; ++k) \
;     acc[ai][bj][m][n] = __builtin_amdgcn_mfma_f32_16x16x32_bf16(Bt[n][k], At[m][k], acc[ai][bj][m][n], 0, 0, 0); __builtin_amdgcn_s_setprio(0); } while (0)
; #define G_WAIT_L(n) asm volatile("s_waitcnt lgkmcnt(" #n ")" ::: "memory")
; #define G_BAR __builtin_amdgcn_s_barrier()
; #define G_SCHED __builtin_amdgcn_sched_barrier(0)
; template <int GP> DI void gemm_phase(const Params& p, int l, int which, char* smem, int wv) {
;     ...
;     for (int t = 0; t < cnk; t += 2) {
;       const bool last = (t == cnk - 2);
;       const char* a1 = cA + (size_t)(t + 1) * kstep;
;       const char* a2 = last ? nA : cA + (size_t)(t + 2) * kstep; const char* b2 = last ? nB : cB + (size_t)(t + 2) * kstep;
;       const char* a3 = a2 + kstep; const char* b3 = b2 + kstep;
;       if (last) {
; #pragma unroll
;         for (int i = 0; i < 2; ++i) { vb0[i] = voffB(i, 0, n32); vb1[i] = voffB(i, 1, n32); }
;       }
;       G_LDB(B0, 0, 0); G_SCHED; G_LDA(At, 0, 0); G_STAGE(G_SA(1, 1), a1 + hstep, voffA);
;       G_WAIT_L(8); G_BAR; G_WAIT_L(0); G_MMA(0, 0, At, B0); G_BAR; G_SCHED;
;       G_LDB(B1, 0, 1); G_STAGE(G_SB(0, 0), b2, vb0);
;       G_BAR; G_WAIT_L(0); G_MMA(0, 1, At, B1); G_BAR;
;       G_LDA(At, 0, 1); G_STAGE(G_SA(0, 0), a2, voffA);
;       G_BAR; G_WAIT_L(0); G_MMA(1, 0, At, B0); G_BAR; G_SCHED;
.LBB0_149:
	v_add_u32_e32 v135, 0x10000, v166
	s_add_u32 s61, s8, s26
	ds_read_b128 v[168:171], v135
	ds_read_b128 v[172:175], v135 offset:1024
	ds_read_b128 v[176:179], v135 offset:2048
	ds_read_b128 v[180:183], v135 offset:3072
	s_addc_u32 s62, s9, s27
	s_and_b64 s[30:31], s[28:29], exec
	s_cselect_b32 s31, s11, s62
	s_cselect_b32 s30, s57, s61
	s_add_u32 s61, s6, s26
	s_addc_u32 s62, s7, s27
	s_and_b64 s[28:29], s[28:29], exec
	s_cselect_b32 s28, s59, s61
	s_cselect_b32 s29, s58, s62
	s_mov_b32 m0, s53
	v_lshl_add_u64 v[216:217], s[8:9], 0, v[162:163]
	ds_read_b128 v[184:187], v165
	ds_read_b128 v[188:191], v165 offset:1024
	ds_read_b128 v[192:195], v165 offset:2048
	ds_read_b128 v[196:199], v165 offset:3072
	ds_read_b128 v[200:203], v165 offset:4096
	ds_read_b128 v[204:207], v165 offset:5120
	ds_read_b128 v[208:211], v165 offset:6144
	ds_read_b128 v[212:215], v165 offset:7168
	global_load_lds_dwordx4 v[216:217], off
	v_lshl_add_u64 v[216:217], s[8:9], 0, v[160:161]
	s_mov_b32 m0, s54
	s_nop 0
	global_load_lds_dwordx4 v[216:217], off
	s_nop 0
	s_barrier
	s_waitcnt lgkmcnt(0)
	s_waitcnt lgkmcnt(0)
	v_mfma_f32_16x16x32_bf16 v[62:65], v[168:171], v[184:187], v[62:65]
	v_mfma_f32_16x16x32_bf16 v[58:61], v[176:179], v[184:187], v[58:61]
	v_mfma_f32_16x16x32_bf16 v[54:57], v[168:171], v[192:195], v[54:57]
	v_mfma_f32_16x16x32_bf16 v[50:53], v[176:179], v[192:195], v[50:53]
	v_mfma_f32_16x16x32_bf16 v[46:49], v[168:171], v[200:203], v[46:49]
	v_mfma_f32_16x16x32_bf16 v[42:45], v[176:179], v[200:203], v[42:45]
	v_mfma_f32_16x16x32_bf16 v[38:41], v[168:171], v[208:211], v[38:41]
	v_mfma_f32_16x16x32_bf16 v[34:37], v[176:179], v[208:211], v[34:37]
	v_mfma_f32_16x16x32_bf16 v[62:65], v[172:175], v[188:191], v[62:65]
	v_mfma_f32_16x16x32_bf16 v[58:61], v[180:183], v[188:191], v[58:61]
	v_mfma_f32_16x16x32_bf16 v[54:57], v[172:175], v[196:199], v[54:57]
	v_mfma_f32_16x16x32_bf16 v[50:53], v[180:183], v[196:199], v[50:53]
	v_mfma_f32_16x16x32_bf16 v[46:49], v[172:175], v[204:207], v[46:49]
	v_mfma_f32_16x16x32_bf16 v[42:45], v[180:183], v[204:207], v[42:45]
	v_mfma_f32_16x16x32_bf16 v[38:41], v[172:175], v[212:215], v[38:41]
	v_mfma_f32_16x16x32_bf16 v[34:37], v[180:183], v[212:215], v[34:37]
	s_barrier
	s_mov_b32 m0, s1
	v_add_u32_e32 v135, 0x14000, v166
	ds_read_b128 v[216:219], v135
	ds_read_b128 v[220:223], v135 offset:1024
	ds_read_b128 v[224:227], v135 offset:2048
	ds_read_b128 v[238:241], v135 offset:3072
	global_load_lds_dwordx4 v0, s[28:29]
	s_mov_b32 m0, s3
	v_mov_b32_e32 v137, v1
	global_load_lds_dwordx4 v136, s[28:29]
	s_barrier
	s_waitcnt lgkmcnt(0)
	v_lshl_add_u64 v[228:229], s[28:29], 0, v[0:1]
	v_lshl_add_u64 v[234:235], s[28:29], 0, v[136:137]
	s_waitcnt lgkmcnt(0)
	v_mfma_f32_16x16x32_bf16 v[30:33], v[216:219], v[184:187], v[30:33]
	v_mfma_f32_16x16x32_bf16 v[26:29], v[224:227], v[184:187], v[26:29]
	v_mfma_f32_16x16x32_bf16 v[22:25], v[216:219], v[192:195], v[22:25]
	v_mfma_f32_16x16x32_bf16 v[18:21], v[224:227], v[192:195], v[18:21]
	v_mfma_f32_16x16x32_bf16 v[14:17], v[216:219], v[200:203], v[14:17]
	v_mfma_f32_16x16x32_bf16 v[10:13], v[224:227], v[200:203], v[10:13]
	v_mfma_f32_16x16x32_bf16 v[6:9], v[216:219], v[208:211], v[6:9]
	v_mfma_f32_16x16x32_bf16 v[2:5], v[224:227], v[208:211], v[2:5]
	v_mfma_f32_16x16x32_bf16 v[30:33], v[220:223], v[188:191], v[30:33]
	v_mfma_f32_16x16x32_bf16 v[26:29], v[238:241], v[188:191], v[26:29]
	v_mfma_f32_16x16x32_bf16 v[22:25], v[220:223], v[196:199], v[22:25]
	v_mfma_f32_16x16x32_bf16 v[18:21], v[238:241], v[196:199], v[18:21]
	v_mfma_f32_16x16x32_bf16 v[14:17], v[220:223], v[204:207], v[14:17]
	v_mfma_f32_16x16x32_bf16 v[10:13], v[238:241], v[204:207], v[10:13]
	v_mfma_f32_16x16x32_bf16 v[6:9], v[220:223], v[212:215], v[6:9]
	v_mfma_f32_16x16x32_bf16 v[2:5], v[238:241], v[212:215], v[2:5]
	s_mov_b32 m0, s38
	v_lshl_add_u64 v[242:243], s[30:31], 0, v[130:131]
	s_barrier
	ds_read_b128 v[184:187], v165 offset:16384
	ds_read_b128 v[188:191], v165 offset:17408
	ds_read_b128 v[192:195], v165 offset:18432
	ds_read_b128 v[196:199], v165 offset:19456
	ds_read_b128 v[200:203], v165 offset:20480
	ds_read_b128 v[204:207], v165 offset:21504
	ds_read_b128 v[208:211], v165 offset:22528
	ds_read_b128 v[212:215], v165 offset:23552
	global_load_lds_dwordx4 v[242:243], off
	v_lshl_add_u64 v[244:245], s[30:31], 0, v[132:133]
	s_mov_b32 m0, s5
	s_nop 0
	global_load_lds_dwordx4 v[244:245], off
	s_barrier
	s_waitcnt lgkmcnt(0)
	s_waitcnt lgkmcnt(0)
	v_mfma_f32_16x16x32_bf16 v[66:69], v[168:171], v[184:187], v[66:69]
	v_mfma_f32_16x16x32_bf16 v[70:73], v[176:179], v[184:187], v[70:73]
	v_mfma_f32_16x16x32_bf16 v[74:77], v[168:171], v[192:195], v[74:77]
	v_mfma_f32_16x16x32_bf16 v[78:81], v[176:179], v[192:195], v[78:81]
	v_mfma_f32_16x16x32_bf16 v[82:85], v[168:171], v[200:203], v[82:85]
	v_mfma_f32_16x16x32_bf16 v[86:89], v[176:179], v[200:203], v[86:89]
	v_mfma_f32_16x16x32_bf16 v[90:93], v[168:171], v[208:211], v[90:93]
	v_mfma_f32_16x16x32_bf16 v[98:101], v[176:179], v[208:211], v[98:101]
	v_mfma_f32_16x16x32_bf16 v[66:69], v[172:175], v[188:191], v[66:69]
	v_mfma_f32_16x16x32_bf16 v[70:73], v[180:183], v[188:191], v[70:73]
	v_mfma_f32_16x16x32_bf16 v[74:77], v[172:175], v[196:199], v[74:77]
	v_mfma_f32_16x16x32_bf16 v[78:81], v[180:183], v[196:199], v[78:81]
	v_mfma_f32_16x16x32_bf16 v[82:85], v[172:175], v[204:207], v[82:85]
	v_mfma_f32_16x16x32_bf16 v[86:89], v[180:183], v[204:207], v[86:89]
	v_mfma_f32_16x16x32_bf16 v[90:93], v[172:175], v[212:215], v[90:93]
	v_mfma_f32_16x16x32_bf16 v[98:101], v[180:183], v[212:215], v[98:101]
	s_barrier
; #define G_STAGE(bufoff, gbase, voff) do { _Pragma("unroll") for (int _i = 0; _i < 2; ++_i) \
;     __builtin_amdgcn_global_load_lds((const unsigned*)((const char*)(gbase) + (voff)[_i]), (LAS unsigned*)(lds + (bufoff) + ldsw + _i * 8192), 16, 0, 0); } while (0)
; #define G_LDA(dst, b, h) do { _Pragma("unroll") for (int m = 0; m < 4; ++m) _Pragma("unroll") for (int k = 0; k < 2; ++k) dst[m][k] = *(const LAS bf16x8*)(lds + G_SA(b, h) + aoff + m * 2048 + k * 1024); } while (0)
; #define G_LDB(dst, b, h) do { _Pragma("unroll") for (int n = 0; n < 2; ++n) _Pragma("unroll") for (int k = 0; k < 2; ++k) dst[n][k] = *(const LAS bf16x8*)(lds + G_SB(b, h) + boff + n * 2048 + k * 1024); } while (0)
; #define G_MMA(ai, bj, At, Bt) do { __builtin_amdgcn_s_setprio(1); _Pragma("unroll") for (int m = 0; m < 4; ++m) _Pragma("unroll") for (int n = 0; n < 2; ++n) _Pragma("unroll") for (int k = 0; k < 2; ++k) \
;     acc[ai][bj][m][n] = __builtin_amdgcn_mfma_f32_16x16x32_bf16(Bt[n][k], At[m][k], acc[ai][bj][m][n], 0, 0, 0); __builtin_amdgcn_s_setprio(0); } while (0)
; #define G_WAIT_V(n) asm volatile("s_waitcnt vmcnt(" #n ")" ::: "memory")
; #define G_WAIT_L(n) asm volatile("s_waitcnt lgkmcnt(" #n ")" ::: "memory")
; #define G_BAR __builtin_amdgcn_s_barrier()
; #define G_SCHED __builtin_amdgcn_sched_barrier(0)
; template <int GP> DI void gemm_phase(const Params& p, int l, int which, char* smem, int wv) {
;     ...
;       G_STAGE(G_SB(0, 1), b2, vb1);
;       G_WAIT_V(6); G_BAR; G_MMA(1, 1, At, B1); G_BAR;
;       G_LDB(B0, 1, 0); G_SCHED; G_LDA(At, 1, 0); G_STAGE(G_SA(0, 1), a2 + hstep, voffA);
;       G_WAIT_L(8); G_BAR; G_WAIT_L(0); G_MMA(0, 0, At, B0); G_BAR; G_SCHED;
;       G_LDB(B1, 1, 1); G_STAGE(G_SB(1, 0), b3, vb0);
	s_mov_b32 m0, s41
	v_mov_b32_e32 v135, v1
	global_load_lds_dwordx4 v134, s[28:29]
	s_mov_b32 m0, s42
	v_mov_b32_e32 v155, v1
	global_load_lds_dwordx4 v154, s[28:29]
	s_waitcnt vmcnt(6)
	v_lshl_add_u64 v[246:247], s[28:29], 0, v[134:135]
	v_lshl_add_u64 v[248:249], s[28:29], 0, v[154:155]
	s_barrier
	v_mfma_f32_16x16x32_bf16 v[94:97], v[216:219], v[184:187], v[94:97]
	v_mfma_f32_16x16x32_bf16 v[102:105], v[224:227], v[184:187], v[102:105]
	v_mfma_f32_16x16x32_bf16 v[106:109], v[216:219], v[192:195], v[106:109]
	v_mfma_f32_16x16x32_bf16 v[110:113], v[224:227], v[192:195], v[110:113]
	v_mfma_f32_16x16x32_bf16 v[114:117], v[216:219], v[200:203], v[114:117]
	v_mfma_f32_16x16x32_bf16 v[118:121], v[224:227], v[200:203], v[118:121]
	v_mfma_f32_16x16x32_bf16 v[122:125], v[216:219], v[208:211], v[122:125]
	v_mfma_f32_16x16x32_bf16 v[126:129], v[224:227], v[208:211], v[126:129]
	v_mfma_f32_16x16x32_bf16 v[94:97], v[220:223], v[188:191], v[94:97]
	v_mfma_f32_16x16x32_bf16 v[102:105], v[238:241], v[188:191], v[102:105]
	v_mfma_f32_16x16x32_bf16 v[106:109], v[220:223], v[196:199], v[106:109]
	v_mfma_f32_16x16x32_bf16 v[110:113], v[238:241], v[196:199], v[110:113]
	v_mfma_f32_16x16x32_bf16 v[114:117], v[220:223], v[204:207], v[114:117]
	v_mfma_f32_16x16x32_bf16 v[118:121], v[238:241], v[204:207], v[118:121]
	v_mfma_f32_16x16x32_bf16 v[122:125], v[220:223], v[212:215], v[122:125]
	v_mfma_f32_16x16x32_bf16 v[126:129], v[238:241], v[212:215], v[126:129]
	v_add_u32_e32 v135, 0x18000, v166
	s_barrier
	ds_read_b128 v[168:171], v135
	ds_read_b128 v[172:175], v135 offset:1024
	ds_read_b128 v[176:179], v135 offset:2048
	ds_read_b128 v[180:183], v135 offset:3072
	s_add_u32 s28, s30, 0x80000
	s_addc_u32 s29, s31, 0
	s_mov_b32 m0, s43
	v_lshl_add_u64 v[216:217], s[28:29], 0, v[130:131]
	ds_read_b128 v[184:187], v165 offset:32768
	ds_read_b128 v[188:191], v165 offset:33792
	ds_read_b128 v[192:195], v165 offset:34816
	ds_read_b128 v[196:199], v165 offset:35840
	ds_read_b128 v[200:203], v165 offset:36864
	ds_read_b128 v[204:207], v165 offset:37888
	ds_read_b128 v[208:211], v165 offset:38912
	ds_read_b128 v[212:215], v165 offset:39936
	global_load_lds_dwordx4 v[216:217], off
	v_lshl_add_u64 v[216:217], s[28:29], 0, v[132:133]
	s_mov_b32 m0, s44
	s_nop 0
	global_load_lds_dwordx4 v[216:217], off
	s_nop 0
	s_barrier
	s_waitcnt lgkmcnt(0)
	s_waitcnt lgkmcnt(0)
	v_mfma_f32_16x16x32_bf16 v[62:65], v[168:171], v[184:187], v[62:65]
	v_mfma_f32_16x16x32_bf16 v[58:61], v[176:179], v[184:187], v[58:61]
	v_mfma_f32_16x16x32_bf16 v[54:57], v[168:171], v[192:195], v[54:57]
	v_mfma_f32_16x16x32_bf16 v[50:53], v[176:179], v[192:195], v[50:53]
	v_mfma_f32_16x16x32_bf16 v[46:49], v[168:171], v[200:203], v[46:49]
	v_mfma_f32_16x16x32_bf16 v[42:45], v[176:179], v[200:203], v[42:45]
	v_mfma_f32_16x16x32_bf16 v[38:41], v[168:171], v[208:211], v[38:41]
	v_mfma_f32_16x16x32_bf16 v[34:37], v[176:179], v[208:211], v[34:37]
	v_mfma_f32_16x16x32_bf16 v[62:65], v[172:175], v[188:191], v[62:65]
	v_mfma_f32_16x16x32_bf16 v[58:61], v[180:183], v[188:191], v[58:61]
	v_mfma_f32_16x16x32_bf16 v[54:57], v[172:175], v[196:199], v[54:57]
	v_mfma_f32_16x16x32_bf16 v[50:53], v[180:183], v[196:199], v[50:53]
	v_mfma_f32_16x16x32_bf16 v[46:49], v[172:175], v[204:207], v[46:49]
	v_mfma_f32_16x16x32_bf16 v[42:45], v[180:183], v[204:207], v[42:45]
	v_mfma_f32_16x16x32_bf16 v[38:41], v[172:175], v[212:215], v[38:41]
	v_mfma_f32_16x16x32_bf16 v[34:37], v[180:183], v[212:215], v[34:37]
	s_barrier
	s_mov_b32 m0, s45
	v_add_u32_e32 v135, 0x1c000, v166
	v_lshl_add_u64 v[228:229], v[228:229], 0, s[74:75]
	ds_read_b128 v[216:219], v135
	ds_read_b128 v[220:223], v135 offset:1024
	ds_read_b128 v[224:227], v135 offset:2048
	ds_read_b128 v[238:241], v135 offset:3072
	global_load_lds_dwordx4 v[228:229], off
	v_lshl_add_u64 v[228:229], v[234:235], 0, s[74:75]
	s_mov_b32 m0, s46
	s_nop 0
	global_load_lds_dwordx4 v[228:229], off
	s_barrier
; #define G_STAGE(bufoff, gbase, voff) do { _Pragma("unroll") for (int _i = 0; _i < 2; ++_i) \
;     __builtin_amdgcn_global_load_lds((const unsigned*)((const char*)(gbase) + (voff)[_i]), (LAS unsigned*)(lds + (bufoff) + ldsw + _i * 8192), 16, 0, 0); } while (0)
; #define G_LDA(dst, b, h) do { _Pragma("unroll") for (int m = 0; m < 4; ++m) _Pragma("unroll") for (int k = 0; k < 2; ++k) dst[m][k] = *(const LAS bf16x8*)(lds + G_SA(b, h) + aoff + m * 2048 + k * 1024); } while (0)
; #define G_MMA(ai, bj, At, Bt) do { __builtin_amdgcn_s_setprio(1); _Pragma("unroll") for (int m = 0; m < 4; ++m) _Pragma("unroll") for (int n = 0; n < 2; ++n) _Pragma("unroll") for (int k = 0; k < 2; ++k) \
;     acc[ai][bj][m][n] = __builtin_amdgcn_mfma_f32_16x16x32_bf16(Bt[n][k], At[m][k], acc[ai][bj][m][n], 0, 0, 0); __builtin_amdgcn_s_setprio(0); } while (0)
; #define G_WAIT_V(n) asm volatile("s_waitcnt vmcnt(" #n ")" ::: "memory")
; #define G_WAIT_L(n) asm volatile("s_waitcnt lgkmcnt(" #n ")" ::: "memory")
; #define G_BAR __builtin_amdgcn_s_barrier()
; #define G_SCHED __builtin_amdgcn_sched_barrier(0)
; template <int GP> DI void gemm_phase(const Params& p, int l, int which, char* smem, int wv) {
;     ...
;       G_BAR; G_WAIT_L(0); G_MMA(0, 1, At, B1); G_BAR;
;       G_LDA(At, 1, 1); G_STAGE(G_SA(1, 0), a3, voffA);
;       G_BAR; G_WAIT_L(0); G_MMA(1, 0, At, B0); G_BAR; G_SCHED;
;       G_STAGE(G_SB(1, 1), b3, vb1);
;       G_WAIT_V(6); G_BAR; G_MMA(1, 1, At, B1); G_BAR;
;     }
;     if (GP == 0) {
;       const int m0 = cmt * 256, n0 = cnt_ * 256;
;       const bool isctx = (cmt % 9) == 0;
;       const int head = wc >> 1;
;       const int n128 = cnt_ * 2 + head;
;       const int rowl0 = wr * 64 + fr;
;       if (which) {
;         const int colb = n0 + head * 128 + (wc & 1) * 32 + fq * 8;
;         u16* ybase = isctx ? p.ypart + ((size_t)(ck0 >> 8) * 1024 + (size_t)(cmt / 9) * 256) * DM : p.y + (size_t)m0 * DM;
	s_waitcnt lgkmcnt(0)
	s_waitcnt lgkmcnt(0)
	v_mfma_f32_16x16x32_bf16 v[30:33], v[216:219], v[184:187], v[30:33]
	v_mfma_f32_16x16x32_bf16 v[26:29], v[224:227], v[184:187], v[26:29]
	v_mfma_f32_16x16x32_bf16 v[22:25], v[216:219], v[192:195], v[22:25]
	v_mfma_f32_16x16x32_bf16 v[18:21], v[224:227], v[192:195], v[18:21]
	v_mfma_f32_16x16x32_bf16 v[14:17], v[216:219], v[200:203], v[14:17]
	v_mfma_f32_16x16x32_bf16 v[10:13], v[224:227], v[200:203], v[10:13]
	v_mfma_f32_16x16x32_bf16 v[6:9], v[216:219], v[208:211], v[6:9]
	v_mfma_f32_16x16x32_bf16 v[2:5], v[224:227], v[208:211], v[2:5]
	v_mfma_f32_16x16x32_bf16 v[30:33], v[220:223], v[188:191], v[30:33]
	v_mfma_f32_16x16x32_bf16 v[26:29], v[238:241], v[188:191], v[26:29]
	v_mfma_f32_16x16x32_bf16 v[22:25], v[220:223], v[196:199], v[22:25]
	v_mfma_f32_16x16x32_bf16 v[18:21], v[238:241], v[196:199], v[18:21]
	v_mfma_f32_16x16x32_bf16 v[14:17], v[220:223], v[204:207], v[14:17]
	v_mfma_f32_16x16x32_bf16 v[10:13], v[238:241], v[204:207], v[10:13]
	v_mfma_f32_16x16x32_bf16 v[6:9], v[220:223], v[212:215], v[6:9]
	v_mfma_f32_16x16x32_bf16 v[2:5], v[238:241], v[212:215], v[2:5]
	s_mov_b32 m0, s48
	v_lshl_add_u64 v[228:229], v[242:243], 0, s[74:75]
	s_barrier
	ds_read_b128 v[184:187], v165 offset:49152
	ds_read_b128 v[188:191], v165 offset:50176
	ds_read_b128 v[192:195], v165 offset:51200
	ds_read_b128 v[196:199], v165 offset:52224
	ds_read_b128 v[200:203], v165 offset:53248
	ds_read_b128 v[204:207], v165 offset:54272
	ds_read_b128 v[208:211], v165 offset:55296
	ds_read_b128 v[212:215], v165 offset:56320
	global_load_lds_dwordx4 v[228:229], off
	v_lshl_add_u64 v[228:229], v[244:245], 0, s[74:75]
	s_mov_b32 m0, s49
	s_nop 0
	global_load_lds_dwordx4 v[228:229], off
	s_barrier
	s_waitcnt lgkmcnt(0)
	s_waitcnt lgkmcnt(0)
	v_mfma_f32_16x16x32_bf16 v[66:69], v[168:171], v[184:187], v[66:69]
	v_mfma_f32_16x16x32_bf16 v[70:73], v[176:179], v[184:187], v[70:73]
	v_mfma_f32_16x16x32_bf16 v[74:77], v[168:171], v[192:195], v[74:77]
	v_mfma_f32_16x16x32_bf16 v[78:81], v[176:179], v[192:195], v[78:81]
	v_mfma_f32_16x16x32_bf16 v[82:85], v[168:171], v[200:203], v[82:85]
	v_mfma_f32_16x16x32_bf16 v[86:89], v[176:179], v[200:203], v[86:89]
	v_mfma_f32_16x16x32_bf16 v[90:93], v[168:171], v[208:211], v[90:93]
	v_mfma_f32_16x16x32_bf16 v[98:101], v[176:179], v[208:211], v[98:101]
	v_mfma_f32_16x16x32_bf16 v[66:69], v[172:175], v[188:191], v[66:69]
	v_mfma_f32_16x16x32_bf16 v[70:73], v[180:183], v[188:191], v[70:73]
	v_mfma_f32_16x16x32_bf16 v[74:77], v[172:175], v[196:199], v[74:77]
	v_mfma_f32_16x16x32_bf16 v[78:81], v[180:183], v[196:199], v[78:81]
	v_mfma_f32_16x16x32_bf16 v[82:85], v[172:175], v[204:207], v[82:85]
	v_mfma_f32_16x16x32_bf16 v[86:89], v[180:183], v[204:207], v[86:89]
	v_mfma_f32_16x16x32_bf16 v[90:93], v[172:175], v[212:215], v[90:93]
	v_mfma_f32_16x16x32_bf16 v[98:101], v[180:183], v[212:215], v[98:101]
	s_barrier
	s_mov_b32 m0, s50
	v_lshl_add_u64 v[168:169], v[246:247], 0, s[74:75]
	global_load_lds_dwordx4 v[168:169], off
	v_lshl_add_u64 v[168:169], v[248:249], 0, s[74:75]
	s_mov_b32 m0, s52
	s_nop 0
	global_load_lds_dwordx4 v[168:169], off
	s_waitcnt vmcnt(6)
	s_barrier
	v_mfma_f32_16x16x32_bf16 v[94:97], v[216:219], v[184:187], v[94:97]
	v_mfma_f32_16x16x32_bf16 v[102:105], v[224:227], v[184:187], v[102:105]
	v_mfma_f32_16x16x32_bf16 v[106:109], v[216:219], v[192:195], v[106:109]
	v_mfma_f32_16x16x32_bf16 v[110:113], v[224:227], v[192:195], v[110:113]
	v_mfma_f32_16x16x32_bf16 v[114:117], v[216:219], v[200:203], v[114:117]
	v_mfma_f32_16x16x32_bf16 v[118:121], v[224:227], v[200:203], v[118:121]
	v_mfma_f32_16x16x32_bf16 v[122:125], v[216:219], v[208:211], v[122:125]
	v_mfma_f32_16x16x32_bf16 v[126:129], v[224:227], v[208:211], v[126:129]
	v_mfma_f32_16x16x32_bf16 v[94:97], v[220:223], v[188:191], v[94:97]
	v_mfma_f32_16x16x32_bf16 v[102:105], v[238:241], v[188:191], v[102:105]
	v_mfma_f32_16x16x32_bf16 v[106:109], v[220:223], v[196:199], v[106:109]
	v_mfma_f32_16x16x32_bf16 v[110:113], v[238:241], v[196:199], v[110:113]
	v_mfma_f32_16x16x32_bf16 v[114:117], v[220:223], v[204:207], v[114:117]
	v_mfma_f32_16x16x32_bf16 v[118:121], v[238:241], v[204:207], v[118:121]
	v_mfma_f32_16x16x32_bf16 v[122:125], v[220:223], v[212:215], v[122:125]
	v_mfma_f32_16x16x32_bf16 v[126:129], v[238:241], v[212:215], v[126:129]
	s_add_i32 s28, s60, 2
	s_add_u32 s26, s26, 0x100
	s_addc_u32 s27, s27, 0
	v_lshl_add_u64 v[162:163], v[162:163], 0, s[78:79]
	s_cmp_ge_i32 s60, s36
	v_lshl_add_u64 v[160:161], v[160:161], 0, s[78:79]
	s_barrier
	s_cbranch_scc0 .LBB0_147
	s_mul_hi_i32 s11, s2, 0x38e38e39
	s_lshr_b32 s26, s11, 31
	s_ashr_i32 s11, s11, 1
	s_add_i32 s26, s11, s26
	s_mul_i32 s11, s26, 9
	s_sub_i32 s11, s2, s11
	s_cmp_lg_u32 s11, 0
	s_cbranch_scc0 .LBB0_155
	s_lshl_b32 s28, s2, 8
	s_ashr_i32 s29, s28, 31
	s_lshl_b64 s[28:29], s[28:29], 12
	s_add_u32 s28, s94, s28
	s_addc_u32 s29, s95, s29
	s_cbranch_execnz .LBB0_153

; #define G_STAGE(bufoff, gbase, voff) do { _Pragma("unroll") for (int _i = 0; _i < 2; ++_i) \
;     __builtin_amdgcn_global_load_lds((const unsigned*)((const char*)(gbase) + (voff)[_i]), (LAS unsigned*)(lds + (bufoff) + ldsw + _i * 8192), 16, 0, 0); } while (0)
; #define G_LDA(dst, b, h) do { _Pragma("unroll") for (int m = 0; m < 4; ++m) _Pragma("unroll") for (int k = 0; k < 2; ++k) dst[m][k] = *(const LAS bf16x8*)(lds + G_SA(b, h) + aoff + m * 2048 + k * 1024); } while (0)
; #define G_LDB(dst, b, h) do { _Pragma("unroll") for (int n = 0; n < 2; ++n) _Pragma("unroll") for (int k = 0; k < 2; ++k) dst[n][k] = *(const LAS bf16x8*)(lds + G_SB(b, h) + boff + n * 2048 + k * 1024); } while (0)
; #define G_MMA(ai, bj, At, Bt) do { __builtin_amdgcn_s_setprio(1); _Pragma("unroll") for (int m = 0; m < 4; ++m) _Pragma("unroll") for (int n = 0; n < 2; ++n) _Pragma("unroll") for (int k = 0; k < 2; ++k) \
;     acc[ai][bj][m][n] = __builtin_amdgcn_mfma_f32_16x16x32_bf16(Bt[n][k], At[m][k], acc[ai][bj][m][n], 0, 0, 0); __builtin_amdgcn_s_setprio(0); } while (0)
; #define G_WAIT_V(n) asm volatile("s_waitcnt vmcnt(" #n ")" ::: "memory")
; #define G_WAIT_L(n) asm volatile("s_waitcnt lgkmcnt(" #n ")" ::: "memory")
; #define G_BAR __builtin_amdgcn_s_barrier()
; #define G_SCHED __builtin_amdgcn_sched_barrier(0)
; template <int GP> DI void gemm_phase(const Params& p, int l, int which, char* smem, int wv) {
;     ...
;     for (int t = 0; t < cnk; t += 2) {
;       const bool last = (t == cnk - 2);
;       const char* a1 = cA + (size_t)(t + 1) * kstep;
;       const char* a2 = last ? nA : cA + (size_t)(t + 2) * kstep; const char* b2 = last ? nB : cB + (size_t)(t + 2) * kstep;
;       const char* a3 = a2 + kstep; const char* b3 = b2 + kstep;
;       if (last) {
; #pragma unroll
;         for (int i = 0; i < 2; ++i) { vb0[i] = voffB(i, 0, n32); vb1[i] = voffB(i, 1, n32); }
;       }
;       G_LDB(B0, 0, 0); G_SCHED; G_LDA(At, 0, 0); G_STAGE(G_SA(1, 1), a1 + hstep, voffA);
;       G_WAIT_L(8); G_BAR; G_WAIT_L(0); G_MMA(0, 0, At, B0); G_BAR; G_SCHED;
;       G_LDB(B1, 0, 1); G_STAGE(G_SB(0, 0), b2, vb0);
;       G_BAR; G_WAIT_L(0); G_MMA(0, 1, At, B1); G_BAR;
;       G_LDA(At, 0, 1); G_STAGE(G_SA(0, 0), a2, voffA);
;       G_BAR; G_WAIT_L(0); G_MMA(1, 0, At, B0); G_BAR; G_SCHED;
;       G_STAGE(G_SB(0, 1), b2, vb1);
;       G_WAIT_V(6); G_BAR; G_MMA(1, 1, At, B1); G_BAR;
.LBB0_209:
	s_add_u32 s8, s28, s2
	v_add_u32_e32 v228, 0x10000, v212
	s_addc_u32 s9, s29, s3
	s_add_u32 s100, s8, 0x80080
	s_addc_u32 s101, s9, 0
	ds_read_b128 v[148:151], v228
	ds_read_b128 v[152:155], v228 offset:1024
	ds_read_b128 v[156:159], v228 offset:2048
	ds_read_b128 v[160:163], v228 offset:3072
	s_add_u32 s52, s8, 0x100
	s_addc_u32 s53, s9, 0
	s_and_b64 s[8:9], s[6:7], exec
	s_cselect_b32 s9, s10, s53
	s_cselect_b32 s8, s11, s52
	s_add_u32 s52, s74, s2
	s_addc_u32 s53, s75, s3
	s_and_b64 s[6:7], s[6:7], exec
	s_cselect_b32 s7, s37, s53
	s_cselect_b32 s6, s39, s52
	s_add_i32 m0, s23, 0xc000
	ds_read_b128 v[164:167], v211
	ds_read_b128 v[168:171], v211 offset:1024
	ds_read_b128 v[172:175], v211 offset:2048
	ds_read_b128 v[176:179], v211 offset:3072
	ds_read_b128 v[180:183], v211 offset:4096
	ds_read_b128 v[184:187], v211 offset:5120
	ds_read_b128 v[188:191], v211 offset:6144
	ds_read_b128 v[192:195], v211 offset:7168
	global_load_lds_dwordx4 v138, s[100:101]
	s_add_i32 m0, s23, 0xe000
	s_nop 0
	global_load_lds_dwordx4 v140, s[100:101]
	s_nop 0
	s_barrier
	s_waitcnt lgkmcnt(0)
	s_waitcnt lgkmcnt(0)
	v_mfma_f32_16x16x32_bf16 v[62:65], v[148:151], v[164:167], v[62:65]
	v_mfma_f32_16x16x32_bf16 v[58:61], v[156:159], v[164:167], v[58:61]
	v_mfma_f32_16x16x32_bf16 v[54:57], v[148:151], v[172:175], v[54:57]
	v_mfma_f32_16x16x32_bf16 v[50:53], v[156:159], v[172:175], v[50:53]
	v_mfma_f32_16x16x32_bf16 v[46:49], v[148:151], v[180:183], v[46:49]
	v_mfma_f32_16x16x32_bf16 v[42:45], v[156:159], v[180:183], v[42:45]
	v_mfma_f32_16x16x32_bf16 v[38:41], v[148:151], v[188:191], v[38:41]
	v_mfma_f32_16x16x32_bf16 v[34:37], v[156:159], v[188:191], v[34:37]
	v_mfma_f32_16x16x32_bf16 v[62:65], v[152:155], v[168:171], v[62:65]
	v_mfma_f32_16x16x32_bf16 v[58:61], v[160:163], v[168:171], v[58:61]
	v_mfma_f32_16x16x32_bf16 v[54:57], v[152:155], v[176:179], v[54:57]
	v_mfma_f32_16x16x32_bf16 v[50:53], v[160:163], v[176:179], v[50:53]
	v_mfma_f32_16x16x32_bf16 v[46:49], v[152:155], v[184:187], v[46:49]
	v_mfma_f32_16x16x32_bf16 v[42:45], v[160:163], v[184:187], v[42:45]
	v_mfma_f32_16x16x32_bf16 v[38:41], v[152:155], v[192:195], v[38:41]
	v_mfma_f32_16x16x32_bf16 v[34:37], v[160:163], v[192:195], v[34:37]
	s_barrier
	s_mov_b32 m0, s25
	ds_read_b128 v[196:199], v228 offset:16384
	ds_read_b128 v[200:203], v228 offset:17408
	ds_read_b128 v[204:207], v228 offset:18432
	ds_read_b128 v[238:241], v228 offset:19456
	global_load_lds_dwordx4 v0, s[6:7]
	s_mov_b32 m0, s58
	s_nop 0
	global_load_lds_dwordx4 v136, s[6:7]
	s_barrier
	s_waitcnt lgkmcnt(0)
	s_waitcnt lgkmcnt(0)
	v_mfma_f32_16x16x32_bf16 v[30:33], v[196:199], v[164:167], v[30:33]
	v_mfma_f32_16x16x32_bf16 v[26:29], v[204:207], v[164:167], v[26:29]
	v_mfma_f32_16x16x32_bf16 v[22:25], v[196:199], v[172:175], v[22:25]
	v_mfma_f32_16x16x32_bf16 v[18:21], v[204:207], v[172:175], v[18:21]
	v_mfma_f32_16x16x32_bf16 v[14:17], v[196:199], v[180:183], v[14:17]
	v_mfma_f32_16x16x32_bf16 v[10:13], v[204:207], v[180:183], v[10:13]
	v_mfma_f32_16x16x32_bf16 v[6:9], v[196:199], v[188:191], v[6:9]
	v_mfma_f32_16x16x32_bf16 v[2:5], v[204:207], v[188:191], v[2:5]
	v_mfma_f32_16x16x32_bf16 v[30:33], v[200:203], v[168:171], v[30:33]
	v_mfma_f32_16x16x32_bf16 v[26:29], v[238:241], v[168:171], v[26:29]
	v_mfma_f32_16x16x32_bf16 v[22:25], v[200:203], v[176:179], v[22:25]
	v_mfma_f32_16x16x32_bf16 v[18:21], v[238:241], v[176:179], v[18:21]
	v_mfma_f32_16x16x32_bf16 v[14:17], v[200:203], v[184:187], v[14:17]
	v_mfma_f32_16x16x32_bf16 v[10:13], v[238:241], v[184:187], v[10:13]
	v_mfma_f32_16x16x32_bf16 v[6:9], v[200:203], v[192:195], v[6:9]
	v_mfma_f32_16x16x32_bf16 v[2:5], v[238:241], v[192:195], v[2:5]
	s_mov_b32 m0, s23
	s_barrier
	ds_read_b128 v[164:167], v211 offset:16384
	ds_read_b128 v[168:171], v211 offset:17408
	ds_read_b128 v[172:175], v211 offset:18432
	ds_read_b128 v[176:179], v211 offset:19456
	ds_read_b128 v[180:183], v211 offset:20480
	ds_read_b128 v[184:187], v211 offset:21504
	ds_read_b128 v[188:191], v211 offset:22528
	ds_read_b128 v[192:195], v211 offset:23552
	global_load_lds_dwordx4 v132, s[8:9]
	s_mov_b32 m0, s59
	s_nop 0
	global_load_lds_dwordx4 v134, s[8:9]
	s_barrier
	s_waitcnt lgkmcnt(0)
	s_waitcnt lgkmcnt(0)
	v_mfma_f32_16x16x32_bf16 v[66:69], v[148:151], v[164:167], v[66:69]
	v_mfma_f32_16x16x32_bf16 v[70:73], v[156:159], v[164:167], v[70:73]
	v_mfma_f32_16x16x32_bf16 v[74:77], v[148:151], v[172:175], v[74:77]
	v_mfma_f32_16x16x32_bf16 v[78:81], v[156:159], v[172:175], v[78:81]
	v_mfma_f32_16x16x32_bf16 v[82:85], v[148:151], v[180:183], v[82:85]
	v_mfma_f32_16x16x32_bf16 v[86:89], v[156:159], v[180:183], v[86:89]
	v_mfma_f32_16x16x32_bf16 v[90:93], v[148:151], v[188:191], v[90:93]
	v_mfma_f32_16x16x32_bf16 v[94:97], v[156:159], v[188:191], v[94:97]
	v_mfma_f32_16x16x32_bf16 v[66:69], v[152:155], v[168:171], v[66:69]
	v_mfma_f32_16x16x32_bf16 v[70:73], v[160:163], v[168:171], v[70:73]
	v_mfma_f32_16x16x32_bf16 v[74:77], v[152:155], v[176:179], v[74:77]
	v_mfma_f32_16x16x32_bf16 v[78:81], v[160:163], v[176:179], v[78:81]
	v_mfma_f32_16x16x32_bf16 v[82:85], v[152:155], v[184:187], v[82:85]
	v_mfma_f32_16x16x32_bf16 v[86:89], v[160:163], v[184:187], v[86:89]
	v_mfma_f32_16x16x32_bf16 v[90:93], v[152:155], v[192:195], v[90:93]
	v_mfma_f32_16x16x32_bf16 v[94:97], v[160:163], v[192:195], v[94:97]
	s_barrier
	s_mov_b32 m0, s60
	s_nop 0
	global_load_lds_dwordx4 v130, s[6:7]
	s_mov_b32 m0, s61
	s_nop 0
	global_load_lds_dwordx4 v142, s[6:7]
	s_waitcnt vmcnt(6)
	s_barrier
; #define G_STAGE(bufoff, gbase, voff) do { _Pragma("unroll") for (int _i = 0; _i < 2; ++_i) \
;     __builtin_amdgcn_global_load_lds((const unsigned*)((const char*)(gbase) + (voff)[_i]), (LAS unsigned*)(lds + (bufoff) + ldsw + _i * 8192), 16, 0, 0); } while (0)
; #define G_LDA(dst, b, h) do { _Pragma("unroll") for (int m = 0; m < 4; ++m) _Pragma("unroll") for (int k = 0; k < 2; ++k) dst[m][k] = *(const LAS bf16x8*)(lds + G_SA(b, h) + aoff + m * 2048 + k * 1024); } while (0)
; #define G_LDB(dst, b, h) do { _Pragma("unroll") for (int n = 0; n < 2; ++n) _Pragma("unroll") for (int k = 0; k < 2; ++k) dst[n][k] = *(const LAS bf16x8*)(lds + G_SB(b, h) + boff + n * 2048 + k * 1024); } while (0)
; #define G_MMA(ai, bj, At, Bt) do { __builtin_amdgcn_s_setprio(1); _Pragma("unroll") for (int m = 0; m < 4; ++m) _Pragma("unroll") for (int n = 0; n < 2; ++n) _Pragma("unroll") for (int k = 0; k < 2; ++k) \
;     acc[ai][bj][m][n] = __builtin_amdgcn_mfma_f32_16x16x32_bf16(Bt[n][k], At[m][k], acc[ai][bj][m][n], 0, 0, 0); __builtin_amdgcn_s_setprio(0); } while (0)
; #define G_WAIT_V(n) asm volatile("s_waitcnt vmcnt(" #n ")" ::: "memory")
; #define G_WAIT_L(n) asm volatile("s_waitcnt lgkmcnt(" #n ")" ::: "memory")
; #define G_BAR __builtin_amdgcn_s_barrier()
; #define G_SCHED __builtin_amdgcn_sched_barrier(0)
; template <int GP> DI void gemm_phase(const Params& p, int l, int which, char* smem, int wv) {
;     ...
;       G_WAIT_V(6); G_BAR; G_MMA(1, 1, At, B1); G_BAR;
;       G_LDB(B0, 1, 0); G_SCHED; G_LDA(At, 1, 0); G_STAGE(G_SA(0, 1), a2 + hstep, voffA);
;       G_WAIT_L(8); G_BAR; G_WAIT_L(0); G_MMA(0, 0, At, B0); G_BAR; G_SCHED;
;       G_LDB(B1, 1, 1); G_STAGE(G_SB(1, 0), b3, vb0);
	v_mfma_f32_16x16x32_bf16 v[98:101], v[196:199], v[164:167], v[98:101]
	v_mfma_f32_16x16x32_bf16 v[102:105], v[204:207], v[164:167], v[102:105]
	v_mfma_f32_16x16x32_bf16 v[106:109], v[196:199], v[172:175], v[106:109]
	v_mfma_f32_16x16x32_bf16 v[110:113], v[204:207], v[172:175], v[110:113]
	v_mfma_f32_16x16x32_bf16 v[114:117], v[196:199], v[180:183], v[114:117]
	v_mfma_f32_16x16x32_bf16 v[118:121], v[204:207], v[180:183], v[118:121]
	v_mfma_f32_16x16x32_bf16 v[122:125], v[196:199], v[188:191], v[122:125]
	v_mfma_f32_16x16x32_bf16 v[126:129], v[204:207], v[188:191], v[126:129]
	v_mfma_f32_16x16x32_bf16 v[98:101], v[200:203], v[168:171], v[98:101]
	v_mfma_f32_16x16x32_bf16 v[102:105], v[238:241], v[168:171], v[102:105]
	v_mfma_f32_16x16x32_bf16 v[106:109], v[200:203], v[176:179], v[106:109]
	v_mfma_f32_16x16x32_bf16 v[110:113], v[238:241], v[176:179], v[110:113]
	v_mfma_f32_16x16x32_bf16 v[114:117], v[200:203], v[184:187], v[114:117]
	v_mfma_f32_16x16x32_bf16 v[118:121], v[238:241], v[184:187], v[118:121]
	v_mfma_f32_16x16x32_bf16 v[122:125], v[200:203], v[192:195], v[122:125]
	v_mfma_f32_16x16x32_bf16 v[126:129], v[238:241], v[192:195], v[126:129]
	s_barrier
	ds_read_b128 v[148:151], v228 offset:32768
	ds_read_b128 v[152:155], v228 offset:33792
	ds_read_b128 v[156:159], v228 offset:34816
	ds_read_b128 v[160:163], v228 offset:35840
	s_add_u32 s100, s8, 0x80000
	s_addc_u32 s101, s9, 0
	s_mov_b32 m0, s62
	ds_read_b128 v[164:167], v211 offset:32768
	ds_read_b128 v[168:171], v211 offset:33792
	ds_read_b128 v[172:175], v211 offset:34816
	ds_read_b128 v[176:179], v211 offset:35840
	ds_read_b128 v[180:183], v211 offset:36864
	ds_read_b128 v[184:187], v211 offset:37888
	ds_read_b128 v[188:191], v211 offset:38912
	ds_read_b128 v[192:195], v211 offset:39936
	global_load_lds_dwordx4 v132, s[100:101]
	s_mov_b32 m0, s63
	s_nop 0
	global_load_lds_dwordx4 v134, s[100:101]
	s_nop 0
	s_barrier
	s_waitcnt lgkmcnt(0)
	s_waitcnt lgkmcnt(0)
	v_mfma_f32_16x16x32_bf16 v[62:65], v[148:151], v[164:167], v[62:65]
	v_mfma_f32_16x16x32_bf16 v[58:61], v[156:159], v[164:167], v[58:61]
	v_mfma_f32_16x16x32_bf16 v[54:57], v[148:151], v[172:175], v[54:57]
	v_mfma_f32_16x16x32_bf16 v[50:53], v[156:159], v[172:175], v[50:53]
	v_mfma_f32_16x16x32_bf16 v[46:49], v[148:151], v[180:183], v[46:49]
	v_mfma_f32_16x16x32_bf16 v[42:45], v[156:159], v[180:183], v[42:45]
	v_mfma_f32_16x16x32_bf16 v[38:41], v[148:151], v[188:191], v[38:41]
	v_mfma_f32_16x16x32_bf16 v[34:37], v[156:159], v[188:191], v[34:37]
	v_mfma_f32_16x16x32_bf16 v[62:65], v[152:155], v[168:171], v[62:65]
	v_mfma_f32_16x16x32_bf16 v[58:61], v[160:163], v[168:171], v[58:61]
	v_mfma_f32_16x16x32_bf16 v[54:57], v[152:155], v[176:179], v[54:57]
	v_mfma_f32_16x16x32_bf16 v[50:53], v[160:163], v[176:179], v[50:53]
	v_mfma_f32_16x16x32_bf16 v[46:49], v[152:155], v[184:187], v[46:49]
	v_mfma_f32_16x16x32_bf16 v[42:45], v[160:163], v[184:187], v[42:45]
	v_mfma_f32_16x16x32_bf16 v[38:41], v[152:155], v[192:195], v[38:41]
	v_mfma_f32_16x16x32_bf16 v[34:37], v[160:163], v[192:195], v[34:37]
	s_barrier
	s_mov_b32 m0, s21
	s_add_u32 s100, s6, s16
	s_addc_u32 s101, s7, s17
	ds_read_b128 v[196:199], v228 offset:49152
	ds_read_b128 v[200:203], v228 offset:50176
	ds_read_b128 v[204:207], v228 offset:51200
	ds_read_b128 v[238:241], v228 offset:52224
	global_load_lds_dwordx4 v0, s[100:101]
	s_mov_b32 m0, s64
	s_nop 0
	global_load_lds_dwordx4 v136, s[100:101]
	s_barrier
; #define G_STAGE(bufoff, gbase, voff) do { _Pragma("unroll") for (int _i = 0; _i < 2; ++_i) \
;     __builtin_amdgcn_global_load_lds((const unsigned*)((const char*)(gbase) + (voff)[_i]), (LAS unsigned*)(lds + (bufoff) + ldsw + _i * 8192), 16, 0, 0); } while (0)
; #define G_LDA(dst, b, h) do { _Pragma("unroll") for (int m = 0; m < 4; ++m) _Pragma("unroll") for (int k = 0; k < 2; ++k) dst[m][k] = *(const LAS bf16x8*)(lds + G_SA(b, h) + aoff + m * 2048 + k * 1024); } while (0)
; #define G_MMA(ai, bj, At, Bt) do { __builtin_amdgcn_s_setprio(1); _Pragma("unroll") for (int m = 0; m < 4; ++m) _Pragma("unroll") for (int n = 0; n < 2; ++n) _Pragma("unroll") for (int k = 0; k < 2; ++k) \
;     acc[ai][bj][m][n] = __builtin_amdgcn_mfma_f32_16x16x32_bf16(Bt[n][k], At[m][k], acc[ai][bj][m][n], 0, 0, 0); __builtin_amdgcn_s_setprio(0); } while (0)
; #define G_WAIT_V(n) asm volatile("s_waitcnt vmcnt(" #n ")" ::: "memory")
; #define G_WAIT_L(n) asm volatile("s_waitcnt lgkmcnt(" #n ")" ::: "memory")
; #define G_BAR __builtin_amdgcn_s_barrier()
; #define G_SCHED __builtin_amdgcn_sched_barrier(0)
; template <int GP> DI void gemm_phase(const Params& p, int l, int which, char* smem, int wv) {
;     ...
;       G_BAR; G_WAIT_L(0); G_MMA(0, 1, At, B1); G_BAR;
;       G_LDA(At, 1, 1); G_STAGE(G_SA(1, 0), a3, voffA);
;       G_BAR; G_WAIT_L(0); G_MMA(1, 0, At, B0); G_BAR; G_SCHED;
;       G_STAGE(G_SB(1, 1), b3, vb1);
;       G_WAIT_V(6); G_BAR; G_MMA(1, 1, At, B1); G_BAR;
;     }
	s_waitcnt lgkmcnt(0)
	s_waitcnt lgkmcnt(0)
	v_mfma_f32_16x16x32_bf16 v[30:33], v[196:199], v[164:167], v[30:33]
	v_mfma_f32_16x16x32_bf16 v[26:29], v[204:207], v[164:167], v[26:29]
	v_mfma_f32_16x16x32_bf16 v[22:25], v[196:199], v[172:175], v[22:25]
	v_mfma_f32_16x16x32_bf16 v[18:21], v[204:207], v[172:175], v[18:21]
	v_mfma_f32_16x16x32_bf16 v[14:17], v[196:199], v[180:183], v[14:17]
	v_mfma_f32_16x16x32_bf16 v[10:13], v[204:207], v[180:183], v[10:13]
	v_mfma_f32_16x16x32_bf16 v[6:9], v[196:199], v[188:191], v[6:9]
	v_mfma_f32_16x16x32_bf16 v[2:5], v[204:207], v[188:191], v[2:5]
	v_mfma_f32_16x16x32_bf16 v[30:33], v[200:203], v[168:171], v[30:33]
	v_mfma_f32_16x16x32_bf16 v[26:29], v[238:241], v[168:171], v[26:29]
	v_mfma_f32_16x16x32_bf16 v[22:25], v[200:203], v[176:179], v[22:25]
	v_mfma_f32_16x16x32_bf16 v[18:21], v[238:241], v[176:179], v[18:21]
	v_mfma_f32_16x16x32_bf16 v[14:17], v[200:203], v[184:187], v[14:17]
	v_mfma_f32_16x16x32_bf16 v[10:13], v[238:241], v[184:187], v[10:13]
	v_mfma_f32_16x16x32_bf16 v[6:9], v[200:203], v[192:195], v[6:9]
	v_mfma_f32_16x16x32_bf16 v[2:5], v[238:241], v[192:195], v[2:5]
	s_mov_b32 m0, s65
	s_add_u32 s100, s8, s16
	s_addc_u32 s101, s9, s17
	s_barrier
	ds_read_b128 v[164:167], v211 offset:49152
	ds_read_b128 v[168:171], v211 offset:50176
	ds_read_b128 v[172:175], v211 offset:51200
	ds_read_b128 v[176:179], v211 offset:52224
	ds_read_b128 v[180:183], v211 offset:53248
	ds_read_b128 v[184:187], v211 offset:54272
	ds_read_b128 v[188:191], v211 offset:55296
	ds_read_b128 v[192:195], v211 offset:56320
	global_load_lds_dwordx4 v132, s[100:101]
	s_mov_b32 m0, s66
	s_nop 0
	global_load_lds_dwordx4 v134, s[100:101]
	s_barrier
	s_waitcnt lgkmcnt(0)
	s_waitcnt lgkmcnt(0)
	v_mfma_f32_16x16x32_bf16 v[66:69], v[148:151], v[164:167], v[66:69]
	v_mfma_f32_16x16x32_bf16 v[70:73], v[156:159], v[164:167], v[70:73]
	v_mfma_f32_16x16x32_bf16 v[74:77], v[148:151], v[172:175], v[74:77]
	v_mfma_f32_16x16x32_bf16 v[78:81], v[156:159], v[172:175], v[78:81]
	v_mfma_f32_16x16x32_bf16 v[82:85], v[148:151], v[180:183], v[82:85]
	v_mfma_f32_16x16x32_bf16 v[86:89], v[156:159], v[180:183], v[86:89]
	v_mfma_f32_16x16x32_bf16 v[90:93], v[148:151], v[188:191], v[90:93]
	v_mfma_f32_16x16x32_bf16 v[94:97], v[156:159], v[188:191], v[94:97]
	v_mfma_f32_16x16x32_bf16 v[66:69], v[152:155], v[168:171], v[66:69]
	v_mfma_f32_16x16x32_bf16 v[70:73], v[160:163], v[168:171], v[70:73]
	v_mfma_f32_16x16x32_bf16 v[74:77], v[152:155], v[176:179], v[74:77]
	v_mfma_f32_16x16x32_bf16 v[78:81], v[160:163], v[176:179], v[78:81]
	v_mfma_f32_16x16x32_bf16 v[82:85], v[152:155], v[184:187], v[82:85]
	v_mfma_f32_16x16x32_bf16 v[86:89], v[160:163], v[184:187], v[86:89]
	v_mfma_f32_16x16x32_bf16 v[90:93], v[152:155], v[192:195], v[90:93]
	v_mfma_f32_16x16x32_bf16 v[94:97], v[160:163], v[192:195], v[94:97]
	s_barrier
	s_mov_b32 m0, s67
	s_add_u32 s100, s6, s16
	s_addc_u32 s101, s7, s17
	global_load_lds_dwordx4 v130, s[100:101]
	s_mov_b32 m0, s68
	s_nop 0
	global_load_lds_dwordx4 v142, s[100:101]
	s_waitcnt vmcnt(6)
	s_barrier
	v_mfma_f32_16x16x32_bf16 v[98:101], v[196:199], v[164:167], v[98:101]
	v_mfma_f32_16x16x32_bf16 v[102:105], v[204:207], v[164:167], v[102:105]
	v_mfma_f32_16x16x32_bf16 v[106:109], v[196:199], v[172:175], v[106:109]
	v_mfma_f32_16x16x32_bf16 v[110:113], v[204:207], v[172:175], v[110:113]
	v_mfma_f32_16x16x32_bf16 v[114:117], v[196:199], v[180:183], v[114:117]
	v_mfma_f32_16x16x32_bf16 v[118:121], v[204:207], v[180:183], v[118:121]
	v_mfma_f32_16x16x32_bf16 v[122:125], v[196:199], v[188:191], v[122:125]
	v_mfma_f32_16x16x32_bf16 v[126:129], v[204:207], v[188:191], v[126:129]
	v_mfma_f32_16x16x32_bf16 v[98:101], v[200:203], v[168:171], v[98:101]
	v_mfma_f32_16x16x32_bf16 v[102:105], v[238:241], v[168:171], v[102:105]
	v_mfma_f32_16x16x32_bf16 v[106:109], v[200:203], v[176:179], v[106:109]
	v_mfma_f32_16x16x32_bf16 v[110:113], v[238:241], v[176:179], v[110:113]
	v_mfma_f32_16x16x32_bf16 v[114:117], v[200:203], v[184:187], v[114:117]
	v_mfma_f32_16x16x32_bf16 v[118:121], v[238:241], v[184:187], v[118:121]
	v_mfma_f32_16x16x32_bf16 v[122:125], v[200:203], v[192:195], v[122:125]
	v_mfma_f32_16x16x32_bf16 v[126:129], v[238:241], v[192:195], v[126:129]
	s_add_i32 s50, s50, 2
	s_add_u32 s2, s2, 0x100
	s_addc_u32 s3, s3, 0
	s_cmp_gt_u32 s50, 29
	s_barrier
	s_cbranch_scc1 .LBB0_219
